# tail 40% of the W3A f32->fp8 conversion moved from phase 0 to the 64 workgroups that idle during adaLN chunk 0 (static split)
# baseline (speedup 1.0000x reference)
; #define LAS __attribute__((address_space(3)))
; __global__ void __launch_bounds__(NWAVES * 64, 2) mk_fwd(Args args) {
;     extern __shared__ __attribute__((aligned(16))) unsigned char lds[];
;     Frame F;
;     F.lds = (LAS unsigned char*)lds;
;     F.MISC = (volatile LAS unsigned*)(F.lds + MISC_OFF);
;     F.tid = threadIdx.x; F.lane = F.tid & 63; F.wave = __builtin_amdgcn_readfirstlane(F.tid >> 6);
;     F.G = gridDim.x; { const int bx = blockIdx.x; F.vcu = (F.G % 8 == 0) ? (bx % 8) * (F.G / 8) + bx / 8 : bx; }
_Z6mk_fwd4Args:
	s_mov_b32 s98, 0
	s_movk_i32 s99, 0x19c8
	s_load_dword s33, s[0:1], 0xd8
	s_load_dwordx2 s[94:95], s[0:1], 0xd0
	s_mov_b32 s50, s2
	s_add_u32 s2, s0, 0xd8
	s_addc_u32 s3, s1, 0
	v_readfirstlane_b32 s24, v0
	v_writelane_b32 v252, s2, 0
	s_nop 1
	v_writelane_b32 v252, s3, 1
	s_waitcnt lgkmcnt(0)
	s_and_b32 s3, s33, 7
	s_mov_b32 s2, 0
	s_cmp_lg_u32 s3, 0
	v_writelane_b32 v252, s50, 2
	s_cbranch_scc1 .LBB0_2
	s_ashr_i32 s4, s50, 31
	s_lshr_b32 s4, s4, 29
	s_add_i32 s4, s50, s4
	s_and_b32 s5, s4, -8
	s_ashr_i32 s3, s33, 3
	s_sub_i32 s5, s50, s5
	s_mul_i32 s3, s3, s5
	s_ashr_i32 s4, s4, 3
	s_add_i32 s3, s3, s4
	v_writelane_b32 v252, s3, 2

; #define LAS __attribute__((address_space(3)))
; template <int JOB>
; __device__ __forceinline__ void conv_job(Frame& F, const Args& A, int rank, int nw) {
;     LAS float* scr = (LAS float*)(F.lds + RING_OFF + F.wave * 16896);
;     unsigned char* ws = A.ws;
;     constexpr int I_13 = (D / 128) * (FF / 32), I_2 = (FF / 128) * (D / 32), I_IN = (D / 64) * (NPROJ / 32), I_OUT = (D / 64) * (D / 32);
;     constexpr int N = (JOB == JOB_W1A || JOB == JOB_W3A || JOB == JOB_W1B || JOB == JOB_W3B) ? I_13 : (JOB == JOB_W2A || JOB == JOB_W2B) ? I_2 : (JOB == JOB_WIN) ? I_IN : I_OUT;
;     for (int it = rank; it < N; it += nw) {
;         if constexpr (JOB == JOB_W1A) p0_transpose_item8<1>(A.in[I_W1A], D, FF, ws + WS_W13A, S_W13, scr, it, F.lane);
;         if constexpr (JOB == JOB_W3A) p0_transpose_item8<2>(A.in[I_W3A], D, FF, ws + WS_W13A, S_W13, scr, it, F.lane);
.Lconv_entry:
	v_readlane_b32 s0, v252, 2
	s_lshl_b32 s0, s0, 3
	v_readlane_b32 s1, v252, 38
	s_add_i32 s0, s0, s1
	s_cmpk_gt_i32 s0, 0x2aff
	s_cbranch_scc1 .LBB0_22
	v_readlane_b32 s2, v252, 38
	s_mulk_i32 s2, 0x4200
	v_and_b32_e32 v18, 31, v0
	v_readlane_b32 s68, v252, 3
	s_add_i32 s2, s2, 0
	v_mov_b32_e32 v21, 0
	v_lshlrev_b32_e32 v20, 2, v18
	v_readlane_b32 s70, v252, 5
	v_readlane_b32 s71, v252, 6
	v_lshrrev_b32_e32 v3, 1, v0
	v_add_u32_e32 v2, s2, v20
	v_lshl_add_u64 v[22:23], s[70:71], 0, v[20:21]
	v_and_b32_e32 v20, 16, v3
	v_lshrrev_b32_e32 v19, 5, v162
	s_movk_i32 s2, 0x84
	v_mul_u32_u24_e32 v3, 0x84, v20
	v_mad_u32_u24 v24, v19, s2, v2
	s_lshl_b32 s6, s0, 5
	v_add_u32_e32 v25, v2, v3
	s_lshl_b32 s1, s33, 3
	s_lshl_b32 s7, s33, 8
	s_mov_b32 s8, 0xac00
	s_mov_b32 s9, 0xc3e00000
	v_mov_b32_e32 v26, 0x43e00000
	v_add_u32_e32 v27, 0x400, v24
	v_add_u32_e32 v28, 0x800, v24
	v_add_u32_e32 v29, 0xc00, v24
	v_add_u32_e32 v30, 0x1000, v24
	v_add_u32_e32 v31, 0x1400, v24
	v_add_u32_e32 v32, 0x1800, v24
	v_add_u32_e32 v33, 0x1c00, v24
	v_add_u32_e32 v34, 0x2000, v24
	v_add_u32_e32 v35, 0x2200, v24
	v_add_u32_e32 v36, 0x2400, v24
	v_add_u32_e32 v37, 0x2600, v24
	v_add_u32_e32 v38, 0x2800, v24
	v_add_u32_e32 v39, 0x2a00, v24
	v_add_u32_e32 v40, 0x2c00, v24
	v_add_u32_e32 v41, 0x2e00, v24
	v_add_u32_e32 v42, 0x3000, v24
	v_add_u32_e32 v43, 0x3200, v24
	v_add_u32_e32 v44, 0x3400, v24
	v_add_u32_e32 v45, 0x3600, v24
	v_add_u32_e32 v46, 0x3800, v24
	v_add_u32_e32 v47, 0x3a00, v24
	v_add_u32_e32 v48, 0x3c00, v24
	v_add_u32_e32 v49, 0x3e00, v24
	v_add_u32_e32 v50, 0x400, v25
	v_add_u32_e32 v51, 0x1000, v25
	v_add_u32_e32 v52, 0x1200, v25
	v_add_u32_e32 v53, 0x1400, v25
	v_add_u32_e32 v54, 0x1600, v25
	v_add_u32_e32 v55, 0x2000, v25
	v_add_u32_e32 v56, 0x2400, v25
	v_add_u32_e32 v57, 0x2800, v25
	v_add_u32_e32 v58, 0x3000, v25
	v_add_u32_e32 v59, 0x3200, v25
	v_add_u32_e32 v60, 0x3400, v25
	v_add_u32_e32 v61, 0x3600, v25
	v_add_u32_e32 v62, 0x3800, v25
	s_mov_b32 s14, s6
	s_mov_b32 s15, s0
	v_readlane_b32 s69, v252, 4
	v_readlane_b32 s72, v252, 7
	v_readlane_b32 s73, v252, 8
	v_readlane_b32 s74, v252, 9
	v_readlane_b32 s75, v252, 10
	v_readlane_b32 s76, v252, 11
	v_readlane_b32 s77, v252, 12
	v_readlane_b32 s78, v252, 13
	v_readlane_b32 s79, v252, 14
	v_readlane_b32 s80, v252, 15
	v_readlane_b32 s81, v252, 16
	v_readlane_b32 s82, v252, 17
	v_readlane_b32 s83, v252, 18
	s_cmp_lg_u32 s98, 1
	s_cbranch_scc1 .LBB0_19
	s_add_i32 s0, s0, 5064
	s_lshl_b32 s6, s0, 5
	s_movk_i32 s1, 0x200
	s_movk_i32 s7, 0x4000
	s_branch .Lw3a_pre

; #define GAS __attribute__((address_space(1)))
; #define LAS __attribute__((address_space(3)))
; template <int MODE>
; __device__ __forceinline__ void p0_transpose_item8(const float* W, int K, int N, unsigned char* WT, float scale, LAS float* scr, int item, int lane) {
;     const int nblk = N / 32, kb = item / nblk, nb = item % nblk, k0 = 128 * kb, n0 = 32 * nb;
;     const GAS float* Wg = (const GAS float*)W;
; #pragma unroll
;     for (int h2 = 0; h2 < 2; ++h2) { float ld[32];
; #pragma unroll
;         for (int i = 0; i < 32; ++i) { const int kk = 2 * (i + 32 * h2) + (lane >> 5); ld[i] = __builtin_nontemporal_load(&Wg[(size_t)(k0 + kk) * N + n0 + (lane & 31)]); }
.Lw3a_pre:
	v_readlane_b32 s68, v252, 3
	v_lshlrev_b32_e32 v2, 2, v18
	v_mov_b32_e32 v3, 0
	v_readlane_b32 s72, v252, 7
	v_readlane_b32 s73, v252, 8
	s_mov_b32 s8, 0xac00
	s_mov_b32 s9, 0xc3e00000
	v_lshl_add_u64 v[22:23], s[72:73], 0, v[2:3]
	v_mov_b32_e32 v26, 0x43e00000
	v_add_u32_e32 v27, 0x400, v24
	v_add_u32_e32 v28, 0x800, v24
	v_add_u32_e32 v29, 0xc00, v24
	v_add_u32_e32 v30, 0x1000, v24
	v_add_u32_e32 v31, 0x1400, v24
	v_add_u32_e32 v32, 0x1800, v24
	v_add_u32_e32 v33, 0x1c00, v24
	v_add_u32_e32 v34, 0x2000, v24
	v_add_u32_e32 v35, 0x2200, v24
	v_add_u32_e32 v36, 0x2400, v24
	v_add_u32_e32 v37, 0x2600, v24
	v_add_u32_e32 v38, 0x2800, v24
	v_add_u32_e32 v39, 0x2a00, v24
	v_add_u32_e32 v40, 0x2c00, v24
	v_add_u32_e32 v41, 0x2e00, v24
	v_add_u32_e32 v42, 0x3000, v24
	v_add_u32_e32 v43, 0x3200, v24
	v_add_u32_e32 v44, 0x3400, v24
	v_readlane_b32 s69, v252, 4
	v_readlane_b32 s70, v252, 5
	v_readlane_b32 s71, v252, 6
	v_readlane_b32 s74, v252, 9
	v_readlane_b32 s75, v252, 10
	v_readlane_b32 s76, v252, 11
	v_readlane_b32 s77, v252, 12
	v_readlane_b32 s78, v252, 13
	v_readlane_b32 s79, v252, 14
	v_readlane_b32 s80, v252, 15
	v_readlane_b32 s81, v252, 16
	v_readlane_b32 s82, v252, 17
	v_readlane_b32 s83, v252, 18
.LBB0_21:
	s_mul_hi_i32 s2, s0, 0x2fa0be83
	s_lshr_b32 s3, s2, 31
	s_ashr_i32 s2, s2, 6
	s_add_i32 s3, s2, s3
	s_mul_i32 s4, s3, 0xffffd500
	s_lshl_b32 s2, s3, 7
	s_mulk_i32 s3, 0xfea8
	s_add_i32 s4, s6, s4
	v_or_b32_e32 v62, s2, v19
	s_add_i32 s14, s0, s3
	s_ashr_i32 s5, s4, 31
	v_or_b32_e32 v64, 2, v62
	v_or_b32_e32 v66, 4, v62
	v_or_b32_e32 v68, 6, v62
	v_or_b32_e32 v70, 8, v62
	v_or_b32_e32 v72, 10, v62
	v_or_b32_e32 v74, 12, v62
	v_or_b32_e32 v76, 14, v62
	v_or_b32_e32 v78, 16, v62
	v_or_b32_e32 v80, 18, v62
	v_or_b32_e32 v82, 20, v62
	v_or_b32_e32 v84, 22, v62
	v_or_b32_e32 v86, 24, v62
	v_or_b32_e32 v88, 26, v62
	v_or_b32_e32 v90, 28, v62
	v_or_b32_e32 v92, 30, v62
	v_or_b32_e32 v94, 32, v62
	v_or_b32_e32 v96, 34, v62
	v_or_b32_e32 v98, 36, v62
	v_or_b32_e32 v100, 38, v62
	v_or_b32_e32 v102, 40, v62
	v_or_b32_e32 v104, 42, v62
	v_or_b32_e32 v106, 44, v62
	v_or_b32_e32 v108, 46, v62
	v_or_b32_e32 v110, 48, v62
	v_or_b32_e32 v112, 50, v62
	v_or_b32_e32 v114, 52, v62
	v_or_b32_e32 v116, 54, v62
	v_or_b32_e32 v118, 56, v62
	v_or_b32_e32 v120, 58, v62
	v_or_b32_e32 v122, 60, v62
	v_or_b32_e32 v124, 62, v62
	s_bfe_u32 s15, s14, 0x2001d
	v_lshl_add_u64 v[60:61], s[4:5], 2, v[22:23]
	v_or_b32_e32 v126, 64, v62
	v_or_b32_e32 v128, 0x42, v62
	v_or_b32_e32 v130, 0x44, v62
	v_or_b32_e32 v132, 0x46, v62
	v_or_b32_e32 v134, 0x48, v62
	v_or_b32_e32 v136, 0x4a, v62
	v_or_b32_e32 v138, 0x4c, v62
	v_or_b32_e32 v140, 0x4e, v62
	v_or_b32_e32 v142, 0x50, v62
	v_or_b32_e32 v144, 0x52, v62
	v_or_b32_e32 v146, 0x54, v62
	v_or_b32_e32 v148, 0x56, v62
	v_or_b32_e32 v150, 0x58, v62
	v_or_b32_e32 v152, 0x5a, v62
	v_or_b32_e32 v154, 0x5c, v62
	v_or_b32_e32 v156, 0x5e, v62
	v_or_b32_e32 v158, 0x60, v62
	v_or_b32_e32 v160, 0x62, v62
	v_or_b32_e32 v164, 0x64, v62
	v_or_b32_e32 v166, 0x66, v62
	v_or_b32_e32 v168, 0x68, v62
	v_or_b32_e32 v170, 0x6a, v62
	v_or_b32_e32 v172, 0x6c, v62
	v_or_b32_e32 v174, 0x6e, v62
	v_or_b32_e32 v176, 0x70, v62
	v_or_b32_e32 v178, 0x72, v62
	v_or_b32_e32 v180, 0x74, v62
	v_or_b32_e32 v182, 0x76, v62
	v_or_b32_e32 v184, 0x78, v62
	v_or_b32_e32 v186, 0x7a, v62
	v_or_b32_e32 v188, 0x7c, v62
	v_or_b32_e32 v192, 0x7e, v62
	s_add_i32 s5, s14, s15
	v_mad_i64_i32 v[62:63], s[14:15], v62, s8, v[60:61]
	v_mad_i64_i32 v[64:65], s[14:15], v64, s8, v[60:61]
	v_mad_i64_i32 v[66:67], s[14:15], v66, s8, v[60:61]
	v_mad_i64_i32 v[68:69], s[14:15], v68, s8, v[60:61]
	v_mad_i64_i32 v[70:71], s[14:15], v70, s8, v[60:61]
	v_mad_i64_i32 v[72:73], s[14:15], v72, s8, v[60:61]
	v_mad_i64_i32 v[74:75], s[14:15], v74, s8, v[60:61]
	v_mad_i64_i32 v[76:77], s[14:15], v76, s8, v[60:61]
	v_mad_i64_i32 v[78:79], s[14:15], v78, s8, v[60:61]
	v_mad_i64_i32 v[80:81], s[14:15], v80, s8, v[60:61]
	v_mad_i64_i32 v[82:83], s[14:15], v82, s8, v[60:61]
	v_mad_i64_i32 v[84:85], s[14:15], v84, s8, v[60:61]
	v_mad_i64_i32 v[86:87], s[14:15], v86, s8, v[60:61]
	v_mad_i64_i32 v[88:89], s[14:15], v88, s8, v[60:61]
	v_mad_i64_i32 v[90:91], s[14:15], v90, s8, v[60:61]
	v_mad_i64_i32 v[92:93], s[14:15], v92, s8, v[60:61]
	v_mad_i64_i32 v[94:95], s[14:15], v94, s8, v[60:61]
	v_mad_i64_i32 v[96:97], s[14:15], v96, s8, v[60:61]
	v_mad_i64_i32 v[98:99], s[14:15], v98, s8, v[60:61]
	v_mad_i64_i32 v[100:101], s[14:15], v100, s8, v[60:61]
	v_mad_i64_i32 v[102:103], s[14:15], v102, s8, v[60:61]
	v_mad_i64_i32 v[104:105], s[14:15], v104, s8, v[60:61]
	v_mad_i64_i32 v[106:107], s[14:15], v106, s8, v[60:61]
	v_mad_i64_i32 v[108:109], s[14:15], v108, s8, v[60:61]
	v_mad_i64_i32 v[110:111], s[14:15], v110, s8, v[60:61]
	v_mad_i64_i32 v[112:113], s[14:15], v112, s8, v[60:61]
	v_mad_i64_i32 v[114:115], s[14:15], v114, s8, v[60:61]
	v_mad_i64_i32 v[116:117], s[14:15], v116, s8, v[60:61]
	v_mad_i64_i32 v[118:119], s[14:15], v118, s8, v[60:61]
	v_mad_i64_i32 v[120:121], s[14:15], v120, s8, v[60:61]
	v_mad_i64_i32 v[122:123], s[14:15], v122, s8, v[60:61]
	v_mad_i64_i32 v[124:125], s[14:15], v124, s8, v[60:61]
	v_mad_i64_i32 v[126:127], s[14:15], v126, s8, v[60:61]
	v_mad_i64_i32 v[128:129], s[14:15], v128, s8, v[60:61]
	v_mad_i64_i32 v[130:131], s[14:15], v130, s8, v[60:61]
	v_mad_i64_i32 v[132:133], s[14:15], v132, s8, v[60:61]
	v_mad_i64_i32 v[134:135], s[14:15], v134, s8, v[60:61]
	v_mad_i64_i32 v[136:137], s[14:15], v136, s8, v[60:61]
	v_mad_i64_i32 v[138:139], s[14:15], v138, s8, v[60:61]
	v_mad_i64_i32 v[140:141], s[14:15], v140, s8, v[60:61]
	v_mad_i64_i32 v[142:143], s[14:15], v142, s8, v[60:61]
; #define LDS_WAIT() asm volatile("s_waitcnt lgkmcnt(0)" ::: "memory")
; template <int MODE>
; __device__ __forceinline__ void p0_transpose_item8(const float* W, int K, int N, unsigned char* WT, float scale, LAS float* scr, int item, int lane) {
;     ...
;     for (int h2 = 0; h2 < 2; ++h2) { float ld[32];
; #pragma unroll
;         for (int i = 0; i < 32; ++i) { const int kk = 2 * (i + 32 * h2) + (lane >> 5); ld[i] = __builtin_nontemporal_load(&Wg[(size_t)(k0 + kk) * N + n0 + (lane & 31)]); }
; #pragma unroll
;         for (int i = 0; i < 32; ++i) { const int kk = 2 * (i + 32 * h2) + (lane >> 5); scr[kk * 33 + (lane & 31)] = ld[i]; } }
;     LDS_WAIT(); asm volatile("" ::: "memory");
	v_mad_i64_i32 v[144:145], s[14:15], v144, s8, v[60:61]
	v_mad_i64_i32 v[146:147], s[14:15], v146, s8, v[60:61]
	v_mad_i64_i32 v[148:149], s[14:15], v148, s8, v[60:61]
	v_mad_i64_i32 v[150:151], s[14:15], v150, s8, v[60:61]
	v_mad_i64_i32 v[152:153], s[14:15], v152, s8, v[60:61]
	v_mad_i64_i32 v[154:155], s[14:15], v154, s8, v[60:61]
	v_mad_i64_i32 v[156:157], s[14:15], v156, s8, v[60:61]
	v_mad_i64_i32 v[158:159], s[14:15], v158, s8, v[60:61]
	v_mad_i64_i32 v[160:161], s[14:15], v160, s8, v[60:61]
	v_mad_i64_i32 v[164:165], s[14:15], v164, s8, v[60:61]
	v_mad_i64_i32 v[166:167], s[14:15], v166, s8, v[60:61]
	v_mad_i64_i32 v[168:169], s[14:15], v168, s8, v[60:61]
	v_mad_i64_i32 v[170:171], s[14:15], v170, s8, v[60:61]
	v_mad_i64_i32 v[172:173], s[14:15], v172, s8, v[60:61]
	v_mad_i64_i32 v[174:175], s[14:15], v174, s8, v[60:61]
	v_mad_i64_i32 v[176:177], s[14:15], v176, s8, v[60:61]
	v_mad_i64_i32 v[178:179], s[14:15], v178, s8, v[60:61]
	v_mad_i64_i32 v[180:181], s[14:15], v180, s8, v[60:61]
	v_mad_i64_i32 v[182:183], s[14:15], v182, s8, v[60:61]
	v_mad_i64_i32 v[184:185], s[14:15], v184, s8, v[60:61]
	v_mad_i64_i32 v[186:187], s[14:15], v186, s8, v[60:61]
	v_mad_i64_i32 v[188:189], s[14:15], v188, s8, v[60:61]
	v_mad_i64_i32 v[60:61], s[14:15], v192, s8, v[60:61]
	global_load_dword v62, v[62:63], off nt
	s_nop 0
	global_load_dword v63, v[64:65], off nt
	s_nop 0
	global_load_dword v64, v[66:67], off nt
	global_load_dword v65, v[68:69], off nt
	s_nop 0
	global_load_dword v66, v[70:71], off nt
	global_load_dword v67, v[72:73], off nt
	global_load_dword v68, v[74:75], off nt
	global_load_dword v69, v[76:77], off nt
	s_nop 0
	global_load_dword v70, v[78:79], off nt
	global_load_dword v71, v[80:81], off nt
	global_load_dword v72, v[82:83], off nt
	global_load_dword v73, v[84:85], off nt
	global_load_dword v74, v[86:87], off nt
	global_load_dword v75, v[88:89], off nt
	global_load_dword v76, v[90:91], off nt
	global_load_dword v77, v[92:93], off nt
	global_load_dword v78, v[94:95], off nt
	global_load_dword v79, v[96:97], off nt
	global_load_dword v80, v[98:99], off nt
	global_load_dword v81, v[100:101], off nt
	global_load_dword v82, v[102:103], off nt
	global_load_dword v83, v[104:105], off nt
	global_load_dword v84, v[106:107], off nt
	global_load_dword v85, v[108:109], off nt
	global_load_dword v86, v[110:111], off nt
	global_load_dword v87, v[112:113], off nt
	global_load_dword v88, v[114:115], off nt
	global_load_dword v89, v[116:117], off nt
	global_load_dword v90, v[118:119], off nt
	global_load_dword v91, v[120:121], off nt
	global_load_dword v92, v[122:123], off nt
	global_load_dword v93, v[124:125], off nt
	global_load_dword v94, v[126:127], off nt
	global_load_dword v95, v[128:129], off nt
	global_load_dword v96, v[130:131], off nt
	global_load_dword v97, v[132:133], off nt
	global_load_dword v98, v[134:135], off nt
	global_load_dword v99, v[136:137], off nt
	global_load_dword v100, v[138:139], off nt
	global_load_dword v101, v[140:141], off nt
	global_load_dword v102, v[142:143], off nt
	global_load_dword v103, v[144:145], off nt
	global_load_dword v104, v[146:147], off nt
	global_load_dword v105, v[148:149], off nt
	global_load_dword v106, v[150:151], off nt
	global_load_dword v107, v[152:153], off nt
	global_load_dword v108, v[154:155], off nt
	global_load_dword v109, v[156:157], off nt
	global_load_dword v110, v[158:159], off nt
	global_load_dword v111, v[160:161], off nt
	global_load_dword v112, v[164:165], off nt
	global_load_dword v113, v[166:167], off nt
	global_load_dword v114, v[168:169], off nt
	global_load_dword v115, v[170:171], off nt
	global_load_dword v116, v[172:173], off nt
	global_load_dword v117, v[174:175], off nt
	global_load_dword v118, v[176:177], off nt
	global_load_dword v119, v[178:179], off nt
	global_load_dword v120, v[180:181], off nt
	global_load_dword v121, v[182:183], off nt
	global_load_dword v122, v[184:185], off nt
	global_load_dword v123, v[186:187], off nt
	global_load_dword v124, v[188:189], off nt
	global_load_dword v125, v[60:61], off nt
	v_add_u32_e32 v45, 0x3600, v24
	v_add_u32_e32 v46, 0x3800, v24
	v_add_u32_e32 v47, 0x3a00, v24
	v_add_u32_e32 v48, 0x3c00, v24
	v_add_u32_e32 v49, 0x3e00, v24
	s_waitcnt vmcnt(62)
	ds_write2_b32 v24, v62, v63 offset1:66
	s_waitcnt vmcnt(60)
	ds_write2_b32 v24, v64, v65 offset0:132 offset1:198
	s_waitcnt vmcnt(58)
	ds_write2_b32 v27, v66, v67 offset0:8 offset1:74
	s_waitcnt vmcnt(56)
	ds_write2_b32 v27, v68, v69 offset0:140 offset1:206
	s_waitcnt vmcnt(54)
	ds_write2_b32 v28, v70, v71 offset0:16 offset1:82
	s_waitcnt vmcnt(52)
	ds_write2_b32 v28, v72, v73 offset0:148 offset1:214
	s_waitcnt vmcnt(50)
	ds_write2_b32 v29, v74, v75 offset0:24 offset1:90
	s_waitcnt vmcnt(48)
	ds_write2_b32 v29, v76, v77 offset0:156 offset1:222
	s_waitcnt vmcnt(46)
	ds_write2_b32 v30, v78, v79 offset0:32 offset1:98
	s_waitcnt vmcnt(44)
	ds_write2_b32 v30, v80, v81 offset0:164 offset1:230
	s_waitcnt vmcnt(42)
	ds_write2_b32 v31, v82, v83 offset0:40 offset1:106
	s_waitcnt vmcnt(40)
	ds_write2_b32 v31, v84, v85 offset0:172 offset1:238
	s_waitcnt vmcnt(38)
	ds_write2_b32 v32, v86, v87 offset0:48 offset1:114
	s_waitcnt vmcnt(36)
	ds_write2_b32 v32, v88, v89 offset0:180 offset1:246
	s_waitcnt vmcnt(34)
	ds_write2_b32 v33, v90, v91 offset0:56 offset1:122
	s_waitcnt vmcnt(32)
	ds_write2_b32 v33, v92, v93 offset0:188 offset1:254
	s_waitcnt vmcnt(30)
	ds_write2_b32 v34, v94, v95 offset0:64 offset1:130
	s_waitcnt vmcnt(28)
	ds_write2_b32 v35, v96, v97 offset0:68 offset1:134
	s_waitcnt vmcnt(26)
	ds_write2_b32 v36, v98, v99 offset0:72 offset1:138
	s_waitcnt vmcnt(24)
; #define LAS __attribute__((address_space(3)))
; #define LDS_WAIT() asm volatile("s_waitcnt lgkmcnt(0)" ::: "memory")
; template <int MODE>
; __device__ __forceinline__ void p0_transpose_item8(const float* W, int K, int N, unsigned char* WT, float scale, LAS float* scr, int item, int lane) {
;     ...
;     LDS_WAIT(); asm volatile("" ::: "memory");
;     const int n = lane & 31, hf = lane >> 5;
;     const int r0 = (MODE == 0) ? n0 : (n0 / 128) * 256 + (n0 % 128) + (MODE == 2 ? 128 : 0);
; #pragma unroll
;     for (int p = 0; p < 4; ++p) { const int q = 2 * p + hf; const LAS float* s = scr + (16 * q) * 33 + n;
;         v4u o;
;         o.x = pg8::cvt4_fp8(s[0 * 33] * scale, s[1 * 33] * scale, s[2 * 33] * scale, s[3 * 33] * scale);
;         o.y = pg8::cvt4_fp8(s[4 * 33] * scale, s[5 * 33] * scale, s[6 * 33] * scale, s[7 * 33] * scale);
;         o.z = pg8::cvt4_fp8(s[8 * 33] * scale, s[9 * 33] * scale, s[10 * 33] * scale, s[11 * 33] * scale);
;         o.w = pg8::cvt4_fp8(s[12 * 33] * scale, s[13 * 33] * scale, s[14 * 33] * scale, s[15 * 33] * scale);
	ds_write2_b32 v37, v100, v101 offset0:76 offset1:142
	s_waitcnt vmcnt(22)
	ds_write2_b32 v38, v102, v103 offset0:80 offset1:146
	s_waitcnt vmcnt(20)
	ds_write2_b32 v39, v104, v105 offset0:84 offset1:150
	s_waitcnt vmcnt(18)
	ds_write2_b32 v40, v106, v107 offset0:88 offset1:154
	s_waitcnt vmcnt(16)
	ds_write2_b32 v41, v108, v109 offset0:92 offset1:158
	s_waitcnt vmcnt(14)
	ds_write2_b32 v42, v110, v111 offset0:96 offset1:162
	s_waitcnt vmcnt(12)
	ds_write2_b32 v43, v112, v113 offset0:100 offset1:166
	s_waitcnt vmcnt(10)
	ds_write2_b32 v44, v114, v115 offset0:104 offset1:170
	s_waitcnt vmcnt(8)
	ds_write2_b32 v45, v116, v117 offset0:108 offset1:174
	s_waitcnt vmcnt(6)
	ds_write2_b32 v46, v118, v119 offset0:112 offset1:178
	s_waitcnt vmcnt(4)
	ds_write2_b32 v47, v120, v121 offset0:116 offset1:182
	s_waitcnt vmcnt(2)
	ds_write2_b32 v48, v122, v123 offset0:120 offset1:186
	s_waitcnt vmcnt(0)
	ds_write2_b32 v49, v124, v125 offset0:124 offset1:190
	s_bfe_u32 s16, s4, 0x70018
	s_waitcnt lgkmcnt(0)
	v_add_u32_e32 v50, 0x400, v25
	v_add_u32_e32 v51, 0x1000, v25
	v_add_u32_e32 v52, 0x1200, v25
	v_add_u32_e32 v53, 0x1400, v25
	v_add_u32_e32 v54, 0x1600, v25
	v_add_u32_e32 v55, 0x2000, v25
	v_add_u32_e32 v56, 0x2400, v25
	v_add_u32_e32 v57, 0x2800, v25
	v_add_u32_e32 v58, 0x3000, v25
	v_add_u32_e32 v59, 0x3200, v25
	s_add_i32 s16, s4, s16
	v_add_u32_e32 v163, 0x3400, v25
	v_add_u32_e32 v190, 0x3600, v25
	v_add_u32_e32 v191, 0x3800, v25
	s_and_b32 s14, s16, 0xff80
	ds_read2_b32 v[46:47], v25 offset1:33
	ds_read2_b32 v[48:49], v25 offset0:66 offset1:99
	ds_read2_b32 v[62:63], v25 offset0:132 offset1:165
	ds_read2_b32 v[64:65], v25 offset0:198 offset1:231
	ds_read2_b32 v[66:67], v50 offset0:8 offset1:41
	ds_read2_b32 v[68:69], v50 offset0:74 offset1:107
	ds_read2_b32 v[70:71], v50 offset0:140 offset1:173
	ds_read2_b32 v[72:73], v50 offset0:206 offset1:239
	ds_read2_b32 v[74:75], v51 offset0:32 offset1:65
	ds_read2_b32 v[76:77], v51 offset0:98 offset1:131
	ds_read2_b32 v[50:51], v51 offset0:164 offset1:197
	ds_read2_b32 v[78:79], v52 offset0:102 offset1:135
	ds_read2_b32 v[80:81], v53 offset0:40 offset1:73
	ds_read2_b32 v[82:83], v53 offset0:106 offset1:139
	ds_read2_b32 v[52:53], v53 offset0:172 offset1:205
	ds_read2_b32 v[84:85], v54 offset0:110 offset1:143
	ds_read2_b32 v[86:87], v55 offset0:64 offset1:97
	ds_read2_b32 v[88:89], v55 offset0:130 offset1:163
	ds_read2_b32 v[54:55], v55 offset0:196 offset1:229
	ds_read2_b32 v[90:91], v56 offset0:72 offset1:105
	ds_read2_b32 v[92:93], v56 offset0:204 offset1:237
	ds_read2_b32 v[94:95], v56 offset0:6 offset1:39
	ds_read2_b32 v[96:97], v56 offset0:138 offset1:171
	ds_read2_b32 v[98:99], v58 offset0:96 offset1:129
	ds_read2_b32 v[100:101], v59 offset0:100 offset1:133
	ds_read2_b32 v[102:103], v163 offset0:104 offset1:137
	ds_read2_b32 v[104:105], v190 offset0:108 offset1:141
	ds_read2_b32 v[56:57], v57 offset0:14 offset1:47
	ds_read2_b32 v[58:59], v58 offset0:162 offset1:195
	ds_read2_b32 v[106:107], v163 offset0:38 offset1:71
	ds_read2_b32 v[108:109], v163 offset0:170 offset1:203
	ds_read2_b32 v[110:111], v191 offset0:46 offset1:79
	s_sext_i32_i16 s5, s5
	s_sub_i32 s4, s4, s14
	s_waitcnt lgkmcnt(14)
	v_mul_f32_e32 v45, 0x44000000, v46
	v_mul_f32_e32 v46, 0x44000000, v47
	v_mul_f32_e32 v47, 0x44000000, v62
	v_mul_f32_e32 v62, 0x44000000, v63
	v_mul_f32_e32 v63, 0x44000000, v66
	v_mul_f32_e32 v66, 0x44000000, v67
	v_mul_f32_e32 v67, 0x44000000, v70
	v_mul_f32_e32 v70, 0x44000000, v71
	v_mov_b32_e32 v2, 0
	v_mov_b32_e32 v3, 0
	v_mov_b32_e32 v4, 0
	v_mov_b32_e32 v5, 0
	s_lshl_b32 s5, s5, 6
	s_addk_i32 s4, 0x80
	v_mul_f32_e32 v71, 0x44000000, v74
	v_mul_f32_e32 v74, 0x44000000, v75
	v_mul_f32_e32 v50, 0x44000000, v50
	v_mul_f32_e32 v51, 0x44000000, v51
	v_mul_f32_e32 v75, 0x44000000, v80
	v_mul_f32_e32 v80, 0x44000000, v81
	v_mul_f32_e32 v52, 0x44000000, v52
	v_mul_f32_e32 v53, 0x44000000, v53
	v_med3_f32 v45, v45, s9, v26
	v_med3_f32 v46, v46, s9, v26
	v_med3_f32 v47, v47, s9, v26
	v_med3_f32 v62, v62, s9, v26
	v_med3_f32 v63, v63, s9, v26
	v_med3_f32 v66, v66, s9, v26
	v_med3_f32 v67, v67, s9, v26
	v_med3_f32 v70, v70, s9, v26
	v_mov_b32_e32 v6, 0
	v_mov_b32_e32 v7, 0
	v_mov_b32_e32 v8, 0
	v_mov_b32_e32 v9, 0
	s_and_b32 s5, s5, 0xffffff00
	s_and_b32 s4, s4, 0xffff
	v_mul_f32_e32 v81, 0x44000000, v86
	v_mul_f32_e32 v86, 0x44000000, v87
	s_waitcnt lgkmcnt(13)
	v_mul_f32_e32 v54, 0x44000000, v54
	v_mul_f32_e32 v55, 0x44000000, v55
	s_waitcnt lgkmcnt(12)
	v_mul_f32_e32 v87, 0x44000000, v90
	v_mul_f32_e32 v90, 0x44000000, v91
	s_waitcnt lgkmcnt(11)
	v_mul_f32_e32 v91, 0x44000000, v92
	v_mul_f32_e32 v92, 0x44000000, v93
	v_med3_f32 v71, v71, s9, v26
	v_med3_f32 v74, v74, s9, v26
	v_med3_f32 v50, v50, s9, v26
	v_med3_f32 v51, v51, s9, v26
	v_med3_f32 v75, v75, s9, v26
	v_med3_f32 v80, v80, s9, v26
	v_med3_f32 v52, v52, s9, v26
	v_med3_f32 v53, v53, s9, v26
	v_cvt_pk_fp8_f32 v2, v45, v46
	v_cvt_pk_fp8_f32 v3, v47, v62
	v_cvt_pk_fp8_f32 v4, v63, v66
	v_cvt_pk_fp8_f32 v5, v67, v70
	v_mov_b32_e32 v10, 0
	v_mov_b32_e32 v11, 0
	v_mov_b32_e32 v12, 0
	v_mov_b32_e32 v13, 0
	s_add_i32 s5, s5, s4
	s_waitcnt lgkmcnt(8)
; #define GAS __attribute__((address_space(1)))
; #define LAS __attribute__((address_space(3)))
; #define LDS_WAIT() asm volatile("s_waitcnt lgkmcnt(0)" ::: "memory")
; template <int MODE>
; __device__ __forceinline__ void p0_transpose_item8(const float* W, int K, int N, unsigned char* WT, float scale, LAS float* scr, int item, int lane) {
;     ...
;     for (int p = 0; p < 4; ++p) { const int q = 2 * p + hf; const LAS float* s = scr + (16 * q) * 33 + n;
;         v4u o;
;         o.x = pg8::cvt4_fp8(s[0 * 33] * scale, s[1 * 33] * scale, s[2 * 33] * scale, s[3 * 33] * scale);
;         o.y = pg8::cvt4_fp8(s[4 * 33] * scale, s[5 * 33] * scale, s[6 * 33] * scale, s[7 * 33] * scale);
;         o.z = pg8::cvt4_fp8(s[8 * 33] * scale, s[9 * 33] * scale, s[10 * 33] * scale, s[11 * 33] * scale);
;         o.w = pg8::cvt4_fp8(s[12 * 33] * scale, s[13 * 33] * scale, s[14 * 33] * scale, s[15 * 33] * scale);
;         *(GAS v4u*)(WT + (size_t)(r0 + n) * K + k0 + 16 * q) = o; }
;     LDS_WAIT(); asm volatile("" ::: "memory");
; template <int JOB>
; __device__ __forceinline__ void conv_job(Frame& F, const Args& A, int rank, int nw) {
;     ...
;     for (int it = rank; it < N; it += nw) {
	v_mul_f32_e32 v93, 0x44000000, v98
	v_mul_f32_e32 v98, 0x44000000, v99
	s_waitcnt lgkmcnt(7)
	v_mul_f32_e32 v99, 0x44000000, v100
	v_mul_f32_e32 v100, 0x44000000, v101
	s_waitcnt lgkmcnt(6)
	v_mul_f32_e32 v101, 0x44000000, v102
	v_mul_f32_e32 v102, 0x44000000, v103
	s_waitcnt lgkmcnt(5)
	v_mul_f32_e32 v103, 0x44000000, v104
	v_mul_f32_e32 v104, 0x44000000, v105
	v_med3_f32 v81, v81, s9, v26
	v_med3_f32 v86, v86, s9, v26
	v_med3_f32 v54, v54, s9, v26
	v_med3_f32 v55, v55, s9, v26
	v_med3_f32 v87, v87, s9, v26
	v_med3_f32 v90, v90, s9, v26
	v_med3_f32 v91, v91, s9, v26
	v_med3_f32 v92, v92, s9, v26
	v_cvt_pk_fp8_f32 v6, v71, v74
	v_cvt_pk_fp8_f32 v7, v50, v51
	v_cvt_pk_fp8_f32 v8, v75, v80
	v_cvt_pk_fp8_f32 v9, v52, v53
	v_mov_b32_e32 v14, 0
	v_mov_b32_e32 v15, 0
	v_mov_b32_e32 v16, 0
	v_mov_b32_e32 v17, 0
	v_or_b32_e32 v60, s5, v18
	v_mul_f32_e32 v48, 0x44000000, v48
	v_mul_f32_e32 v49, 0x44000000, v49
	v_mul_f32_e32 v64, 0x44000000, v64
	v_mul_f32_e32 v65, 0x44000000, v65
	v_mul_f32_e32 v68, 0x44000000, v68
	v_mul_f32_e32 v69, 0x44000000, v69
	v_mul_f32_e32 v72, 0x44000000, v72
	v_mul_f32_e32 v73, 0x44000000, v73
	v_med3_f32 v93, v93, s9, v26
	v_med3_f32 v98, v98, s9, v26
	v_med3_f32 v99, v99, s9, v26
	v_med3_f32 v100, v100, s9, v26
	v_med3_f32 v101, v101, s9, v26
	v_med3_f32 v102, v102, s9, v26
	v_med3_f32 v103, v103, s9, v26
	v_med3_f32 v104, v104, s9, v26
	v_cvt_pk_fp8_f32 v10, v81, v86
	v_cvt_pk_fp8_f32 v11, v54, v55
	v_cvt_pk_fp8_f32 v12, v87, v90
	v_cvt_pk_fp8_f32 v13, v91, v92
	v_ashrrev_i32_e32 v61, 31, v60
	v_mul_f32_e32 v76, 0x44000000, v76
	v_mul_f32_e32 v77, 0x44000000, v77
	v_mul_f32_e32 v78, 0x44000000, v78
	v_mul_f32_e32 v79, 0x44000000, v79
	v_mul_f32_e32 v82, 0x44000000, v82
	v_mul_f32_e32 v83, 0x44000000, v83
	v_mul_f32_e32 v84, 0x44000000, v84
	v_mul_f32_e32 v85, 0x44000000, v85
	v_med3_f32 v48, v48, s9, v26
	v_med3_f32 v49, v49, s9, v26
	v_med3_f32 v64, v64, s9, v26
	v_med3_f32 v65, v65, s9, v26
	v_med3_f32 v68, v68, s9, v26
	v_med3_f32 v69, v69, s9, v26
	v_med3_f32 v72, v72, s9, v26
	v_med3_f32 v73, v73, s9, v26
	v_cvt_pk_fp8_f32 v14, v93, v98
	v_cvt_pk_fp8_f32 v15, v99, v100
	v_cvt_pk_fp8_f32 v16, v101, v102
	v_cvt_pk_fp8_f32 v17, v103, v104
	v_lshlrev_b64 v[60:61], 12, v[60:61]
	v_mul_f32_e32 v88, 0x44000000, v88
	v_mul_f32_e32 v89, 0x44000000, v89
	v_mul_f32_e32 v94, 0x44000000, v94
	v_mul_f32_e32 v95, 0x44000000, v95
	v_mul_f32_e32 v96, 0x44000000, v96
	v_mul_f32_e32 v97, 0x44000000, v97
	s_waitcnt lgkmcnt(4)
	v_mul_f32_e32 v56, 0x44000000, v56
	v_mul_f32_e32 v57, 0x44000000, v57
	v_med3_f32 v76, v76, s9, v26
	v_med3_f32 v77, v77, s9, v26
	v_med3_f32 v78, v78, s9, v26
	v_med3_f32 v79, v79, s9, v26
	v_med3_f32 v82, v82, s9, v26
	v_med3_f32 v83, v83, s9, v26
	v_med3_f32 v84, v84, s9, v26
	v_med3_f32 v85, v85, s9, v26
	v_cvt_pk_fp8_f32 v2, v48, v49 op_sel:[0,0,1]
	v_cvt_pk_fp8_f32 v3, v64, v65 op_sel:[0,0,1]
	v_cvt_pk_fp8_f32 v4, v68, v69 op_sel:[0,0,1]
	v_cvt_pk_fp8_f32 v5, v72, v73 op_sel:[0,0,1]
	s_ashr_i32 s3, s2, 31
	v_lshl_add_u64 v[60:61], s[10:11], 0, v[60:61]
	s_waitcnt lgkmcnt(3)
	v_mul_f32_e32 v58, 0x44000000, v58
	v_mul_f32_e32 v59, 0x44000000, v59
	s_waitcnt lgkmcnt(2)
	v_mul_f32_e32 v105, 0x44000000, v106
	v_mul_f32_e32 v106, 0x44000000, v107
	s_waitcnt lgkmcnt(1)
	v_mul_f32_e32 v107, 0x44000000, v108
	v_mul_f32_e32 v108, 0x44000000, v109
	s_waitcnt lgkmcnt(0)
	v_mul_f32_e32 v109, 0x44000000, v110
	v_mul_f32_e32 v110, 0x44000000, v111
	v_med3_f32 v88, v88, s9, v26
	v_med3_f32 v89, v89, s9, v26
	v_med3_f32 v94, v94, s9, v26
	v_med3_f32 v95, v95, s9, v26
	v_med3_f32 v96, v96, s9, v26
	v_med3_f32 v97, v97, s9, v26
	v_med3_f32 v56, v56, s9, v26
	v_med3_f32 v57, v57, s9, v26
	v_cvt_pk_fp8_f32 v6, v76, v77 op_sel:[0,0,1]
	v_cvt_pk_fp8_f32 v7, v78, v79 op_sel:[0,0,1]
	v_cvt_pk_fp8_f32 v8, v82, v83 op_sel:[0,0,1]
	v_cvt_pk_fp8_f32 v9, v84, v85 op_sel:[0,0,1]
	v_lshl_add_u64 v[60:61], v[60:61], 0, s[2:3]
	v_med3_f32 v58, v58, s9, v26
	v_med3_f32 v59, v59, s9, v26
	v_med3_f32 v105, v105, s9, v26
	v_med3_f32 v106, v106, s9, v26
	v_med3_f32 v107, v107, s9, v26
	v_med3_f32 v108, v108, s9, v26
	v_med3_f32 v109, v109, s9, v26
	v_med3_f32 v110, v110, s9, v26
	v_cvt_pk_fp8_f32 v10, v88, v89 op_sel:[0,0,1]
	v_cvt_pk_fp8_f32 v11, v94, v95 op_sel:[0,0,1]
	v_cvt_pk_fp8_f32 v12, v96, v97 op_sel:[0,0,1]
	v_cvt_pk_fp8_f32 v13, v56, v57 op_sel:[0,0,1]
	v_lshl_add_u64 v[60:61], v[60:61], 0, v[20:21]
	v_cvt_pk_fp8_f32 v14, v58, v59 op_sel:[0,0,1]
	v_cvt_pk_fp8_f32 v15, v105, v106 op_sel:[0,0,1]
	v_cvt_pk_fp8_f32 v16, v107, v108 op_sel:[0,0,1]
	v_cvt_pk_fp8_f32 v17, v109, v110 op_sel:[0,0,1]
	global_store_dwordx4 v[60:61], v[2:5], off
	global_store_dwordx4 v[60:61], v[6:9], off offset:32
	global_store_dwordx4 v[60:61], v[10:13], off offset:64
	global_store_dwordx4 v[60:61], v[14:17], off offset:96
	s_waitcnt lgkmcnt(0)
	s_add_i32 s0, s0, s1
	s_add_i32 s6, s6, s7
	s_cmp_lt_i32 s0, s99
	s_cbranch_scc1 .LBB0_21
.LBB0_22:
	s_cmp_eq_u32 s98, 1
	s_cbranch_scc0 .Lp0_cont
	s_mov_b32 s98, 2
	v_readlane_b32 s4, v253, 0
	v_readlane_b32 s5, v253, 1
	v_readlane_b32 s9, v253, 2
	v_readlane_b32 s18, v253, 3
	s_nop 7
	s_branch .LBB0_97

; #define SEAM(k) do { if (IN(k) && IN((k) + 1)) xcd_barrier(bar); } while (0)
; __global__ void __launch_bounds__(NWAVES * 64, 2) mk_fwd(Args args) {
;     ...
;         for (int rep = 0; rep < REPS(0); ++rep) { if (rep) xcd_barrier(bar);  csilu_phase(F, args); { const int rank = F.vcu * NWAVES + F.wave, nw = F.G * NWAVES; conv_job<JOB_W1A>(F, args, rank, nw); conv_job<JOB_W3A>(F, args, rank, nw); }  } } SEAM(0);
;     if (IN(1)) {
; #pragma unroll
;         for (int rep = 0; rep < REPS(1); ++rep) { if (rep) xcd_barrier(bar); mod_chunk_partials(F, args, 0, F.vcu, F.G); } } SEAM(1);
.Lp1_call:
	s_mov_b32 s98, 1
	v_writelane_b32 v253, s4, 0
	v_writelane_b32 v253, s5, 1
	v_writelane_b32 v253, s9, 2
	v_writelane_b32 v253, s18, 3
	s_movk_i32 s99, 0x2b00
	s_branch .Lconv_entry

; __global__ void __launch_bounds__(NWAVES * 64, 2) mk_fwd(Args args) {
	.amdhsa_kernel _Z6mk_fwd4Args
		.amdhsa_group_segment_fixed_size 0
		.amdhsa_private_segment_fixed_size 0
		.amdhsa_kernarg_size 472
		.amdhsa_user_sgpr_count 2
		.amdhsa_user_sgpr_dispatch_ptr 0
		.amdhsa_user_sgpr_queue_ptr 0
		.amdhsa_user_sgpr_kernarg_segment_ptr 1
		.amdhsa_user_sgpr_dispatch_id 0
		.amdhsa_user_sgpr_kernarg_preload_length 0
		.amdhsa_user_sgpr_kernarg_preload_offset 0
		.amdhsa_user_sgpr_private_segment_size 0
		.amdhsa_uses_dynamic_stack 0
		.amdhsa_enable_private_segment 0
		.amdhsa_system_sgpr_workgroup_id_x 1
		.amdhsa_system_sgpr_workgroup_id_y 0
		.amdhsa_system_sgpr_workgroup_id_z 0
		.amdhsa_system_sgpr_workgroup_info 0
		.amdhsa_system_vgpr_workitem_id 0
		.amdhsa_next_free_vgpr 256
		.amdhsa_next_free_sgpr 102
		.amdhsa_accum_offset 256
		.amdhsa_reserve_vcc 1
		.amdhsa_float_round_mode_32 0
		.amdhsa_float_round_mode_16_64 0
		.amdhsa_float_denorm_mode_32 3
		.amdhsa_float_denorm_mode_16_64 3
		.amdhsa_dx10_clamp 1
		.amdhsa_ieee_mode 1
		.amdhsa_fp16_overflow 0
		.amdhsa_tg_split 0
		.amdhsa_exception_fp_ieee_invalid_op 0
		.amdhsa_exception_fp_denorm_src 0
		.amdhsa_exception_fp_ieee_div_zero 0
		.amdhsa_exception_fp_ieee_overflow 0
		.amdhsa_exception_fp_ieee_underflow 0
		.amdhsa_exception_fp_ieee_inexact 0
		.amdhsa_exception_int_div_zero 0
	.end_amdhsa_kernel

; __global__ void __launch_bounds__(NWAVES * 64, 2) mk_fwd(Args args) {
.Lfunc_end0:
	.size	_Z6mk_fwd4Args, .Lfunc_end0-_Z6mk_fwd4Args
	.set _Z6mk_fwd4Args.num_vgpr, 256
	.set _Z6mk_fwd4Args.num_agpr, 0
	.set _Z6mk_fwd4Args.numbered_sgpr, 102
	.set _Z6mk_fwd4Args.num_named_barrier, 0
	.set _Z6mk_fwd4Args.private_seg_size, 0
	.set _Z6mk_fwd4Args.uses_vcc, 1
	.set _Z6mk_fwd4Args.uses_flat_scratch, 0
	.set _Z6mk_fwd4Args.has_dyn_sized_stack, 0
	.set _Z6mk_fwd4Args.has_recursion, 0
	.set _Z6mk_fwd4Args.has_indirect_call, 0

; __global__ void __launch_bounds__(NWAVES * 64, 2) mk_fwd(Args args) {
amdhsa.kernels:
  - .agpr_count:     0
    .args:
      - .offset:         0
        .size:           216
        .value_kind:     by_value
      - .offset:         216
        .size:           4
        .value_kind:     hidden_block_count_x
      - .offset:         220
        .size:           4
        .value_kind:     hidden_block_count_y
      - .offset:         224
        .size:           4
        .value_kind:     hidden_block_count_z
      - .offset:         228
        .size:           2
        .value_kind:     hidden_group_size_x
      - .offset:         230
        .size:           2
        .value_kind:     hidden_group_size_y
      - .offset:         232
        .size:           2
        .value_kind:     hidden_group_size_z
      - .offset:         234
        .size:           2
        .value_kind:     hidden_remainder_x
      - .offset:         236
        .size:           2
        .value_kind:     hidden_remainder_y
      - .offset:         238
        .size:           2
        .value_kind:     hidden_remainder_z
      - .offset:         256
        .size:           8
        .value_kind:     hidden_global_offset_x
      - .offset:         264
        .size:           8
        .value_kind:     hidden_global_offset_y
      - .offset:         272
        .size:           8
        .value_kind:     hidden_global_offset_z
      - .offset:         280
        .size:           2
        .value_kind:     hidden_grid_dims
      - .offset:         336
        .size:           4
        .value_kind:     hidden_dynamic_lds_size
    .group_segment_fixed_size: 0
    .kernarg_segment_align: 8
    .kernarg_segment_size: 472
    .language:       OpenCL C
    .language_version:
      - 2
      - 0
    .max_flat_workgroup_size: 512
    .name:           _Z6mk_fwd4Args
    .private_segment_fixed_size: 0
    .sgpr_count:     108
    .sgpr_spill_count: 47
    .symbol:         _Z6mk_fwd4Args.kd
    .uniform_work_group_size: 1
    .uses_dynamic_stack: false
    .vgpr_count:     256
    .vgpr_spill_count: 0
    .wavefront_size: 64
